# P3 attention unit epilogue: gate tile prefetched by LDS-DMA at the start of the peeled tail (no exposed gate-load latency in the epilogue)
# baseline (speedup 1.0000x reference)
.LBB0_431:
	s_or_b64 exec, exec, s[2:3]
	s_lshl_b64 s[2:3], s[26:27], 12
	s_add_u32 s2, s61, s2
	s_addc_u32 s3, s62, s3
	s_lshl_b32 s6, s63, 1
	s_add_u32 s2, s2, s6
	v_add_u32_e32 v80, v131, v128
	v_ashrrev_i32_e32 v131, 31, v130
	s_addc_u32 s3, s3, 0
	v_lshlrev_b64 v[64:65], 12, v[130:131]
	v_mul_lo_u32 v66, v155, s56
	v_lshl_add_u64 v[64:65], s[2:3], 0, v[64:65]
	v_add_u32_e32 v81, 0x12000, v66
	v_and_b32_e32 v128, 0xf0, v156
	v_lshrrev_b32_e32 v127, 4, v157
	v_lshl_add_u64 v[78:79], v[64:65], 0, v[128:129]
	v_or_b32_e32 v126, v81, v128
	v_lshlrev_b32_e32 v128, 12, v127
	v_or_b32_e32 v68, 0x8000, v128
	v_mov_b32_e32 v69, v129
	v_or_b32_e32 v72, 0x10000, v128
	v_mov_b32_e32 v73, v129
	v_or_b32_e32 v76, 0x18000, v128
	v_mov_b32_e32 v77, v129
	s_waitcnt lgkmcnt(0)
	v_lshl_add_u64 v[64:65], v[78:79], 0, v[128:129]
	v_or_b32_e32 v66, 0x4000, v128
	v_mov_b32_e32 v67, v129
	v_lshl_add_u64 v[70:71], v[78:79], 0, v[68:69]
	v_or_b32_e32 v68, 0xc000, v128
	v_lshl_add_u64 v[72:73], v[78:79], 0, v[72:73]
	v_or_b32_e32 v74, 0x14000, v128
	v_mov_b32_e32 v75, v129
	v_lshl_add_u64 v[76:77], v[78:79], 0, v[76:77]
	v_or_b32_e32 v128, 0x1c000, v128
	v_lshl_add_u64 v[66:67], v[78:79], 0, v[66:67]
	v_lshl_add_u64 v[68:69], v[78:79], 0, v[68:69]
	v_lshl_add_u64 v[74:75], v[78:79], 0, v[74:75]
	v_lshl_add_u64 v[78:79], v[78:79], 0, v[128:129]
	ds_read_b128 v[82:85], v80
	ds_read_b128 v[118:121], v80 offset:32
	ds_read_b128 v[122:125], v80 offset:64
	ds_read_b128 v[130:133], v80 offset:96
	v_mad_u32_u24 v80, v127, s57, v126
	s_waitcnt lgkmcnt(3)
	v_rcp_f32_e32 v126, v82
	v_lshl_or_b32 v81, v154, 1, v81
	v_mad_u32_u24 v81, v153, s58, v81
	v_rcp_f32_e32 v127, v83
	v_mul_f32_e32 v0, v0, v126
	v_mul_f32_e32 v48, v48, v126
	v_mul_f32_e32 v32, v32, v126
	v_rcp_f32_e32 v128, v84
	v_rcp_f32_e32 v134, v85
	s_waitcnt lgkmcnt(2)
	v_rcp_f32_e32 v118, v118
	v_rcp_f32_e32 v119, v119
	v_rcp_f32_e32 v120, v120
	v_rcp_f32_e32 v121, v121
	s_waitcnt lgkmcnt(1)
	v_rcp_f32_e32 v122, v122
	v_rcp_f32_e32 v123, v123
	v_rcp_f32_e32 v124, v124
	v_rcp_f32_e32 v125, v125
	s_waitcnt lgkmcnt(0)
	v_rcp_f32_e32 v85, v130
	v_rcp_f32_e32 v84, v131
	v_rcp_f32_e32 v83, v132
	v_rcp_f32_e32 v82, v133
	v_readlane_b32 s2, v255, 6
	s_add_i32 s59, s59, s2
	s_cmpk_gt_i32 s59, 0x3ff
	v_readlane_b32 s3, v255, 7
	s_waitcnt vmcnt(0)
	ds_read_u16 v86, v81
	ds_read_u16 v87, v81 offset:64
	ds_read_u16 v88, v81 offset:128
	ds_read_u16 v89, v81 offset:192
	ds_read_u16 v90, v81 offset:272
	ds_read_u16 v91, v81 offset:336
	ds_read_u16 v92, v81 offset:400
	ds_read_u16 v93, v81 offset:464
	s_waitcnt lgkmcnt(7)
	v_lshlrev_b32_e32 v86, 16, v86
	s_waitcnt lgkmcnt(6)
	v_lshlrev_b32_e32 v87, 16, v87
	s_waitcnt lgkmcnt(5)
	v_lshlrev_b32_e32 v88, 16, v88
	v_mul_f32_e32 v0, v0, v86
	v_mul_f32_e32 v48, v48, v87
	v_mul_f32_e32 v32, v32, v88
	v_cvt_pk_bf16_f32 v0, v0, s0
	v_cvt_pk_bf16_f32 v48, v48, s0
	ds_write_b16 v81, v0
	ds_write_b16 v81, v48 offset:64
	v_cvt_pk_bf16_f32 v0, v32, s0
	ds_write_b16 v81, v0 offset:128
	v_mul_f32_e32 v0, v16, v126
	s_waitcnt lgkmcnt(7)
	v_lshlrev_b32_e32 v16, 16, v89
	v_mul_f32_e32 v0, v0, v16
	v_cvt_pk_bf16_f32 v0, v0, s0
	ds_write_b16 v81, v0 offset:192
	v_mul_f32_e32 v0, v1, v127
	s_waitcnt lgkmcnt(7)
	v_lshlrev_b32_e32 v1, 16, v90
	v_mul_f32_e32 v0, v0, v1
	v_cvt_pk_bf16_f32 v0, v0, s0
	ds_write_b16 v81, v0 offset:272
	v_mul_f32_e32 v0, v49, v127
	s_waitcnt lgkmcnt(7)
	v_lshlrev_b32_e32 v1, 16, v91
	v_mul_f32_e32 v0, v0, v1
	v_cvt_pk_bf16_f32 v0, v0, s0
	ds_write_b16 v81, v0 offset:336
	v_mul_f32_e32 v0, v33, v127
	s_waitcnt lgkmcnt(7)
	v_lshlrev_b32_e32 v1, 16, v92
	v_mul_f32_e32 v0, v0, v1
	v_cvt_pk_bf16_f32 v0, v0, s0
	ds_write_b16 v81, v0 offset:400
	v_mul_f32_e32 v0, v17, v127
	s_waitcnt lgkmcnt(7)
	v_lshlrev_b32_e32 v1, 16, v93
	v_mul_f32_e32 v0, v0, v1
	v_cvt_pk_bf16_f32 v0, v0, s0
	ds_write_b16 v81, v0 offset:464
	v_mul_f32_e32 v0, v2, v128
	ds_read_u16 v1, v81 offset:544
	ds_read_u16 v2, v81 offset:608
	ds_read_u16 v16, v81 offset:672
	ds_read_u16 v17, v81 offset:736
	ds_read_u16 v32, v81 offset:816
	ds_read_u16 v33, v81 offset:880
	ds_read_u16 v48, v81 offset:944
	ds_read_u16 v49, v81 offset:1008
	s_waitcnt lgkmcnt(7)
	v_lshlrev_b32_e32 v1, 16, v1
	v_mul_f32_e32 v0, v0, v1
	v_cvt_pk_bf16_f32 v0, v0, s0
	ds_write_b16 v81, v0 offset:544
	v_mul_f32_e32 v0, v50, v128
	s_waitcnt lgkmcnt(7)
	v_lshlrev_b32_e32 v1, 16, v2
	v_mul_f32_e32 v0, v0, v1
	v_cvt_pk_bf16_f32 v0, v0, s0
	ds_write_b16 v81, v0 offset:608
	v_mul_f32_e32 v0, v34, v128
	s_waitcnt lgkmcnt(7)
	v_lshlrev_b32_e32 v1, 16, v16
	v_mul_f32_e32 v0, v0, v1
	v_cvt_pk_bf16_f32 v0, v0, s0
	ds_write_b16 v81, v0 offset:672
	v_mul_f32_e32 v0, v18, v128
	s_waitcnt lgkmcnt(7)
	v_lshlrev_b32_e32 v1, 16, v17
	v_mul_f32_e32 v0, v0, v1
	v_cvt_pk_bf16_f32 v0, v0, s0
	ds_write_b16 v81, v0 offset:736
	v_mul_f32_e32 v0, v3, v134
	s_waitcnt lgkmcnt(7)
	v_lshlrev_b32_e32 v1, 16, v32
	v_mul_f32_e32 v0, v0, v1
	v_cvt_pk_bf16_f32 v0, v0, s0
	ds_write_b16 v81, v0 offset:816
	v_mul_f32_e32 v0, v51, v134
	s_waitcnt lgkmcnt(7)
	v_lshlrev_b32_e32 v1, 16, v33
	v_mul_f32_e32 v0, v0, v1
	v_cvt_pk_bf16_f32 v0, v0, s0
	ds_write_b16 v81, v0 offset:880
	v_mul_f32_e32 v0, v35, v134
	s_waitcnt lgkmcnt(7)
	v_lshlrev_b32_e32 v1, 16, v48
	v_mul_f32_e32 v0, v0, v1
	v_cvt_pk_bf16_f32 v0, v0, s0
	ds_write_b16 v81, v0 offset:944
	v_mul_f32_e32 v0, v19, v134
	s_waitcnt lgkmcnt(7)
	v_lshlrev_b32_e32 v1, 16, v49
	v_mul_f32_e32 v0, v0, v1
	v_cvt_pk_bf16_f32 v0, v0, s0
	ds_write_b16 v81, v0 offset:1008
	v_mul_f32_e32 v0, v4, v118
	ds_read_u16 v1, v81 offset:2176
	ds_read_u16 v2, v81 offset:2240
	ds_read_u16 v3, v81 offset:2304
	ds_read_u16 v4, v81 offset:2368
	ds_read_u16 v16, v81 offset:2448
	ds_read_u16 v17, v81 offset:2512
	ds_read_u16 v18, v81 offset:2576
	ds_read_u16 v19, v81 offset:2640
	s_waitcnt lgkmcnt(7)
	v_lshlrev_b32_e32 v1, 16, v1
	v_mul_f32_e32 v0, v0, v1
	v_cvt_pk_bf16_f32 v0, v0, s0
	ds_write_b16 v81, v0 offset:2176
	v_mul_f32_e32 v0, v52, v118
	s_waitcnt lgkmcnt(7)
	v_lshlrev_b32_e32 v1, 16, v2
	v_mul_f32_e32 v0, v0, v1
	v_cvt_pk_bf16_f32 v0, v0, s0
	ds_write_b16 v81, v0 offset:2240
	v_mul_f32_e32 v0, v36, v118
	s_waitcnt lgkmcnt(7)
	v_lshlrev_b32_e32 v1, 16, v3
	v_mul_f32_e32 v0, v0, v1
	v_cvt_pk_bf16_f32 v0, v0, s0
	ds_write_b16 v81, v0 offset:2304
	v_mul_f32_e32 v0, v20, v118
	s_waitcnt lgkmcnt(7)
	v_lshlrev_b32_e32 v1, 16, v4
	v_mul_f32_e32 v0, v0, v1
	v_cvt_pk_bf16_f32 v0, v0, s0
	ds_write_b16 v81, v0 offset:2368
	v_mul_f32_e32 v0, v5, v119
	s_waitcnt lgkmcnt(7)
	v_lshlrev_b32_e32 v1, 16, v16
	v_mul_f32_e32 v0, v0, v1
	v_cvt_pk_bf16_f32 v0, v0, s0
	ds_write_b16 v81, v0 offset:2448
	v_mul_f32_e32 v0, v53, v119
	s_waitcnt lgkmcnt(7)
	v_lshlrev_b32_e32 v1, 16, v17
	v_mul_f32_e32 v0, v0, v1
	v_cvt_pk_bf16_f32 v0, v0, s0
	ds_write_b16 v81, v0 offset:2512
	v_mul_f32_e32 v0, v37, v119
	s_waitcnt lgkmcnt(7)
	v_lshlrev_b32_e32 v1, 16, v18
	v_mul_f32_e32 v0, v0, v1
	v_cvt_pk_bf16_f32 v0, v0, s0
	ds_write_b16 v81, v0 offset:2576
	v_mul_f32_e32 v0, v21, v119
	s_waitcnt lgkmcnt(7)
	v_lshlrev_b32_e32 v1, 16, v19
	v_mul_f32_e32 v0, v0, v1
	v_cvt_pk_bf16_f32 v0, v0, s0
	ds_write_b16 v81, v0 offset:2640
	v_mul_f32_e32 v0, v6, v120
	ds_read_u16 v1, v81 offset:2720
	ds_read_u16 v2, v81 offset:2784
	ds_read_u16 v3, v81 offset:2848
	ds_read_u16 v4, v81 offset:2912
	ds_read_u16 v5, v81 offset:2992
	ds_read_u16 v6, v81 offset:3056
	ds_read_u16 v16, v81 offset:3120
	ds_read_u16 v17, v81 offset:3184
	s_waitcnt lgkmcnt(7)
	v_lshlrev_b32_e32 v1, 16, v1
	v_mul_f32_e32 v0, v0, v1
	v_cvt_pk_bf16_f32 v0, v0, s0
	ds_write_b16 v81, v0 offset:2720
	v_mul_f32_e32 v0, v54, v120
	s_waitcnt lgkmcnt(7)
	v_lshlrev_b32_e32 v1, 16, v2
	v_mul_f32_e32 v0, v0, v1
	v_cvt_pk_bf16_f32 v0, v0, s0
	ds_write_b16 v81, v0 offset:2784
	v_mul_f32_e32 v0, v38, v120
	s_waitcnt lgkmcnt(7)
	v_lshlrev_b32_e32 v1, 16, v3
	v_mul_f32_e32 v0, v0, v1
	v_cvt_pk_bf16_f32 v0, v0, s0
	ds_write_b16 v81, v0 offset:2848
	v_mul_f32_e32 v0, v22, v120
	s_waitcnt lgkmcnt(7)
	v_lshlrev_b32_e32 v1, 16, v4
	v_mul_f32_e32 v0, v0, v1
	v_cvt_pk_bf16_f32 v0, v0, s0
	ds_write_b16 v81, v0 offset:2912
	v_mul_f32_e32 v0, v7, v121
	s_waitcnt lgkmcnt(7)
	v_lshlrev_b32_e32 v1, 16, v5
	v_mul_f32_e32 v0, v0, v1
	v_cvt_pk_bf16_f32 v0, v0, s0
	ds_write_b16 v81, v0 offset:2992
	v_mul_f32_e32 v0, v55, v121
	s_waitcnt lgkmcnt(7)
	v_lshlrev_b32_e32 v1, 16, v6
	v_mul_f32_e32 v0, v0, v1
	v_cvt_pk_bf16_f32 v0, v0, s0
	ds_write_b16 v81, v0 offset:3056
	v_mul_f32_e32 v0, v39, v121
	s_waitcnt lgkmcnt(7)
	v_lshlrev_b32_e32 v1, 16, v16
	v_mul_f32_e32 v0, v0, v1
	v_cvt_pk_bf16_f32 v0, v0, s0
	ds_write_b16 v81, v0 offset:3120
	v_mul_f32_e32 v0, v23, v121
	s_waitcnt lgkmcnt(7)
	v_lshlrev_b32_e32 v1, 16, v17
	v_mul_f32_e32 v0, v0, v1
	v_cvt_pk_bf16_f32 v0, v0, s0
	ds_write_b16 v81, v0 offset:3184
	v_mul_f32_e32 v0, v8, v122
	ds_read_u16 v1, v81 offset:4352
	ds_read_u16 v2, v81 offset:4416
	ds_read_u16 v3, v81 offset:4480
	ds_read_u16 v4, v81 offset:4544
	ds_read_u16 v5, v81 offset:4624
	ds_read_u16 v6, v81 offset:4688
	ds_read_u16 v7, v81 offset:4752
	ds_read_u16 v8, v81 offset:4816
	s_waitcnt lgkmcnt(7)
	v_lshlrev_b32_e32 v1, 16, v1
	v_mul_f32_e32 v0, v0, v1
	v_cvt_pk_bf16_f32 v0, v0, s0
	ds_write_b16 v81, v0 offset:4352
	v_mul_f32_e32 v0, v56, v122
	s_waitcnt lgkmcnt(7)
	v_lshlrev_b32_e32 v1, 16, v2
	v_mul_f32_e32 v0, v0, v1
	v_cvt_pk_bf16_f32 v0, v0, s0
	ds_write_b16 v81, v0 offset:4416
	v_mul_f32_e32 v0, v40, v122
	s_waitcnt lgkmcnt(7)
	v_lshlrev_b32_e32 v1, 16, v3
	v_mul_f32_e32 v0, v0, v1
	v_cvt_pk_bf16_f32 v0, v0, s0
	ds_write_b16 v81, v0 offset:4480
	v_mul_f32_e32 v0, v24, v122
	s_waitcnt lgkmcnt(7)
	v_lshlrev_b32_e32 v1, 16, v4
	v_mul_f32_e32 v0, v0, v1
	v_cvt_pk_bf16_f32 v0, v0, s0
	ds_write_b16 v81, v0 offset:4544
	v_mul_f32_e32 v0, v9, v123
	s_waitcnt lgkmcnt(7)
	v_lshlrev_b32_e32 v1, 16, v5
	v_mul_f32_e32 v0, v0, v1
	v_cvt_pk_bf16_f32 v0, v0, s0
	ds_write_b16 v81, v0 offset:4624
	v_mul_f32_e32 v0, v57, v123
	s_waitcnt lgkmcnt(7)
	v_lshlrev_b32_e32 v1, 16, v6
	v_mul_f32_e32 v0, v0, v1
	v_cvt_pk_bf16_f32 v0, v0, s0
	ds_write_b16 v81, v0 offset:4688
	v_mul_f32_e32 v0, v41, v123
	s_waitcnt lgkmcnt(7)
	v_lshlrev_b32_e32 v1, 16, v7
	v_mul_f32_e32 v0, v0, v1
	v_cvt_pk_bf16_f32 v0, v0, s0
	ds_write_b16 v81, v0 offset:4752
	v_mul_f32_e32 v0, v25, v123
	s_waitcnt lgkmcnt(7)
	v_lshlrev_b32_e32 v1, 16, v8
	v_mul_f32_e32 v0, v0, v1
	v_cvt_pk_bf16_f32 v0, v0, s0
	ds_write_b16 v81, v0 offset:4816
	ds_read_u16 v1, v81 offset:4896
	ds_read_u16 v2, v81 offset:4960
	ds_read_u16 v3, v81 offset:5024
	ds_read_u16 v4, v81 offset:5088
	ds_read_u16 v5, v81 offset:5168
	ds_read_u16 v6, v81 offset:5232
	ds_read_u16 v7, v81 offset:5296
	ds_read_u16 v8, v81 offset:5360
	v_mul_f32_e32 v0, v10, v124
	s_waitcnt lgkmcnt(7)
	v_lshlrev_b32_e32 v1, 16, v1
	v_mul_f32_e32 v0, v0, v1
	v_cvt_pk_bf16_f32 v0, v0, s0
	ds_write_b16 v81, v0 offset:4896
	v_mul_f32_e32 v0, v58, v124
	s_waitcnt lgkmcnt(7)
	v_lshlrev_b32_e32 v1, 16, v2
	v_mul_f32_e32 v0, v0, v1
	v_cvt_pk_bf16_f32 v0, v0, s0
	ds_write_b16 v81, v0 offset:4960
	v_mul_f32_e32 v0, v42, v124
	s_waitcnt lgkmcnt(7)
	v_lshlrev_b32_e32 v1, 16, v3
	v_mul_f32_e32 v0, v0, v1
	v_cvt_pk_bf16_f32 v0, v0, s0
	ds_write_b16 v81, v0 offset:5024
	v_mul_f32_e32 v0, v26, v124
	s_waitcnt lgkmcnt(7)
	v_lshlrev_b32_e32 v1, 16, v4
	v_mul_f32_e32 v0, v0, v1
	v_cvt_pk_bf16_f32 v0, v0, s0
	ds_write_b16 v81, v0 offset:5088
	v_mul_f32_e32 v0, v11, v125
	s_waitcnt lgkmcnt(7)
	v_lshlrev_b32_e32 v1, 16, v5
	v_mul_f32_e32 v0, v0, v1
	v_cvt_pk_bf16_f32 v0, v0, s0
	ds_write_b16 v81, v0 offset:5168
	v_mul_f32_e32 v0, v59, v125
	s_waitcnt lgkmcnt(7)
	v_lshlrev_b32_e32 v1, 16, v6
	v_mul_f32_e32 v0, v0, v1
	v_cvt_pk_bf16_f32 v0, v0, s0
	ds_write_b16 v81, v0 offset:5232
	v_mul_f32_e32 v0, v43, v125
	s_waitcnt lgkmcnt(7)
	v_lshlrev_b32_e32 v1, 16, v7
	v_mul_f32_e32 v0, v0, v1
	v_cvt_pk_bf16_f32 v0, v0, s0
	ds_write_b16 v81, v0 offset:5296
	v_mul_f32_e32 v0, v27, v125
	s_waitcnt lgkmcnt(7)
	v_lshlrev_b32_e32 v1, 16, v8
	v_mul_f32_e32 v0, v0, v1
	v_cvt_pk_bf16_f32 v0, v0, s0
	ds_write_b16 v81, v0 offset:5360
	ds_read_u16 v1, v81 offset:6528
	ds_read_u16 v2, v81 offset:6592
	ds_read_u16 v3, v81 offset:6656
	ds_read_u16 v4, v81 offset:6720
	ds_read_u16 v5, v81 offset:6800
	ds_read_u16 v6, v81 offset:6864
	ds_read_u16 v7, v81 offset:6928
	ds_read_u16 v8, v81 offset:6992
	v_mul_f32_e32 v0, v12, v85
	s_waitcnt lgkmcnt(7)
	v_lshlrev_b32_e32 v1, 16, v1
	v_mul_f32_e32 v0, v0, v1
	v_cvt_pk_bf16_f32 v0, v0, s0
	ds_write_b16 v81, v0 offset:6528
	v_mul_f32_e32 v0, v60, v85
	s_waitcnt lgkmcnt(7)
	v_lshlrev_b32_e32 v1, 16, v2
	v_mul_f32_e32 v0, v0, v1
	v_cvt_pk_bf16_f32 v0, v0, s0
	ds_write_b16 v81, v0 offset:6592
	v_mul_f32_e32 v0, v44, v85
	s_waitcnt lgkmcnt(7)
	v_lshlrev_b32_e32 v1, 16, v3
	v_mul_f32_e32 v0, v0, v1
	v_cvt_pk_bf16_f32 v0, v0, s0
	ds_write_b16 v81, v0 offset:6656
	v_mul_f32_e32 v0, v28, v85
	s_waitcnt lgkmcnt(7)
	v_lshlrev_b32_e32 v1, 16, v4
	v_mul_f32_e32 v0, v0, v1
	v_cvt_pk_bf16_f32 v0, v0, s0
	ds_write_b16 v81, v0 offset:6720
	v_mul_f32_e32 v0, v13, v84
	s_waitcnt lgkmcnt(7)
	v_lshlrev_b32_e32 v1, 16, v5
	v_mul_f32_e32 v0, v0, v1
	v_cvt_pk_bf16_f32 v0, v0, s0
	ds_write_b16 v81, v0 offset:6800
	v_mul_f32_e32 v0, v61, v84
	s_waitcnt lgkmcnt(7)
	v_lshlrev_b32_e32 v1, 16, v6
	v_mul_f32_e32 v0, v0, v1
	v_cvt_pk_bf16_f32 v0, v0, s0
	ds_write_b16 v81, v0 offset:6864
	v_mul_f32_e32 v0, v45, v84
	s_waitcnt lgkmcnt(7)
	v_lshlrev_b32_e32 v1, 16, v7
	v_mul_f32_e32 v0, v0, v1
	v_cvt_pk_bf16_f32 v0, v0, s0
	ds_write_b16 v81, v0 offset:6928
	v_mul_f32_e32 v0, v29, v84
	s_waitcnt lgkmcnt(7)
	v_lshlrev_b32_e32 v1, 16, v8
	v_mul_f32_e32 v0, v0, v1
	v_cvt_pk_bf16_f32 v0, v0, s0
	ds_write_b16 v81, v0 offset:6992
	ds_read_u16 v1, v81 offset:7072
	ds_read_u16 v2, v81 offset:7136
	ds_read_u16 v3, v81 offset:7200
	ds_read_u16 v4, v81 offset:7264
	ds_read_u16 v5, v81 offset:7344
	ds_read_u16 v6, v81 offset:7408
	ds_read_u16 v7, v81 offset:7472
	ds_read_u16 v8, v81 offset:7536
	v_mul_f32_e32 v0, v14, v83
	s_waitcnt lgkmcnt(7)
	v_lshlrev_b32_e32 v1, 16, v1
	v_mul_f32_e32 v0, v0, v1
	v_cvt_pk_bf16_f32 v0, v0, s0
	ds_write_b16 v81, v0 offset:7072
	v_mul_f32_e32 v0, v62, v83
	s_waitcnt lgkmcnt(7)
	v_lshlrev_b32_e32 v1, 16, v2
	v_mul_f32_e32 v0, v0, v1
	v_cvt_pk_bf16_f32 v0, v0, s0
	ds_write_b16 v81, v0 offset:7136
	v_mul_f32_e32 v0, v46, v83
	s_waitcnt lgkmcnt(7)
	v_lshlrev_b32_e32 v1, 16, v3
	v_mul_f32_e32 v0, v0, v1
	v_cvt_pk_bf16_f32 v0, v0, s0
	ds_write_b16 v81, v0 offset:7200
	v_mul_f32_e32 v0, v30, v83
	s_waitcnt lgkmcnt(7)
	v_lshlrev_b32_e32 v1, 16, v4
	v_mul_f32_e32 v0, v0, v1
	v_cvt_pk_bf16_f32 v0, v0, s0
	ds_write_b16 v81, v0 offset:7264
	v_mul_f32_e32 v0, v15, v82
	s_waitcnt lgkmcnt(7)
	v_lshlrev_b32_e32 v1, 16, v5
	v_mul_f32_e32 v0, v0, v1
	v_cvt_pk_bf16_f32 v0, v0, s0
	ds_write_b16 v81, v0 offset:7344
	v_mul_f32_e32 v0, v63, v82
	s_waitcnt lgkmcnt(7)
	v_lshlrev_b32_e32 v1, 16, v6
	v_mul_f32_e32 v0, v0, v1
	v_cvt_pk_bf16_f32 v0, v0, s0
	ds_write_b16 v81, v0 offset:7408
	v_mul_f32_e32 v0, v47, v82
	s_waitcnt lgkmcnt(7)
	v_lshlrev_b32_e32 v1, 16, v7
	v_mul_f32_e32 v0, v0, v1
	v_cvt_pk_bf16_f32 v0, v0, s0
	ds_write_b16 v81, v0 offset:7472
	v_mul_f32_e32 v0, v31, v82
	s_waitcnt lgkmcnt(7)
	v_lshlrev_b32_e32 v1, 16, v8
	v_mul_f32_e32 v0, v0, v1
	v_cvt_pk_bf16_f32 v0, v0, s0
	ds_write_b16 v81, v0 offset:7536
	ds_read_b128 v[0:3], v80
	ds_read_b128 v[4:7], v80 offset:1088
	ds_read_b128 v[8:11], v80 offset:2176
	s_waitcnt lgkmcnt(2)
	global_store_dwordx4 v[64:65], v[0:3], off
	s_waitcnt lgkmcnt(1)
	global_store_dwordx4 v[66:67], v[4:7], off
	s_waitcnt lgkmcnt(0)
	global_store_dwordx4 v[70:71], v[8:11], off
	ds_read_b128 v[0:3], v80 offset:3264
	ds_read_b128 v[4:7], v80 offset:4352
	ds_read_b128 v[8:11], v80 offset:5440
	ds_read_b128 v[12:15], v80 offset:6528
	ds_read_b128 v[16:19], v80 offset:7616
	s_waitcnt lgkmcnt(4)
	global_store_dwordx4 v[68:69], v[0:3], off
	s_waitcnt lgkmcnt(3)
	global_store_dwordx4 v[72:73], v[4:7], off
	s_waitcnt lgkmcnt(2)
	global_store_dwordx4 v[74:75], v[8:11], off
	s_waitcnt lgkmcnt(1)
	global_store_dwordx4 v[76:77], v[12:15], off
	s_waitcnt lgkmcnt(0)
	global_store_dwordx4 v[78:79], v[16:19], off
	s_barrier
	s_cbranch_scc1 .LBB0_449

.LBB0_443:
	v_mov_b32_e32 v178, v159
	s_nop 1
	v_permlane32_swap_b32_e32 v159, v178
	v_add_f32_e32 v159, v159, v178
	v_readfirstlane_b32 s85, v155
	v_lshlrev_b32_e32 v230, 2, v157
	s_lshl_b64 s[82:83], s[26:27], 12
	s_add_u32 s82, s61, s82
	s_addc_u32 s83, s62, s83
	s_lshl_b32 s84, s63, 1
	s_add_u32 s82, s82, s84
	s_addc_u32 s83, s83, 0
	s_lshl_b32 s84, s85, 17
	s_add_u32 s82, s82, s84
	s_addc_u32 s83, s83, 0
	s_mul_i32 s84, s85, 0x2200
	s_add_u32 s84, s84, 0x12000
	s_add_u32 m0, s84, 0x0
	s_nop 0
	global_load_lds_dword v230, s[82:83]
	s_add_u32 s82, s82, 0x1000
	s_addc_u32 s83, s83, 0
	s_add_u32 m0, s84, 0x110
	s_nop 0
	global_load_lds_dword v230, s[82:83]
	s_add_u32 s82, s82, 0x1000
	s_addc_u32 s83, s83, 0
	s_add_u32 m0, s84, 0x220
	s_nop 0
	global_load_lds_dword v230, s[82:83]
	s_add_u32 s82, s82, 0x1000
	s_addc_u32 s83, s83, 0
	s_add_u32 m0, s84, 0x330
	s_nop 0
	global_load_lds_dword v230, s[82:83]
	s_add_u32 s82, s82, 0x1000
	s_addc_u32 s83, s83, 0
	s_add_u32 m0, s84, 0x440
	s_nop 0
	global_load_lds_dword v230, s[82:83]
	s_add_u32 s82, s82, 0x1000
	s_addc_u32 s83, s83, 0
	s_add_u32 m0, s84, 0x550
	s_nop 0
	global_load_lds_dword v230, s[82:83]
	s_add_u32 s82, s82, 0x1000
	s_addc_u32 s83, s83, 0
	s_add_u32 m0, s84, 0x660
	s_nop 0
	global_load_lds_dword v230, s[82:83]
	s_add_u32 s82, s82, 0x1000
	s_addc_u32 s83, s83, 0
	s_add_u32 m0, s84, 0x770
	s_nop 0
	global_load_lds_dword v230, s[82:83]
	s_add_u32 s82, s82, 0x1000
	s_addc_u32 s83, s83, 0
	s_add_u32 m0, s84, 0x880
	s_nop 0
	global_load_lds_dword v230, s[82:83]
	s_add_u32 s82, s82, 0x1000
	s_addc_u32 s83, s83, 0
	s_add_u32 m0, s84, 0x990
	s_nop 0
	global_load_lds_dword v230, s[82:83]
	s_add_u32 s82, s82, 0x1000
	s_addc_u32 s83, s83, 0
	s_add_u32 m0, s84, 0xaa0
	s_nop 0
	global_load_lds_dword v230, s[82:83]
	s_add_u32 s82, s82, 0x1000
	s_addc_u32 s83, s83, 0
	s_add_u32 m0, s84, 0xbb0
	s_nop 0
	global_load_lds_dword v230, s[82:83]
	s_add_u32 s82, s82, 0x1000
	s_addc_u32 s83, s83, 0
	s_add_u32 m0, s84, 0xcc0
	s_nop 0
	global_load_lds_dword v230, s[82:83]
	s_add_u32 s82, s82, 0x1000
	s_addc_u32 s83, s83, 0
	s_add_u32 m0, s84, 0xdd0
	s_nop 0
	global_load_lds_dword v230, s[82:83]
	s_add_u32 s82, s82, 0x1000
	s_addc_u32 s83, s83, 0
	s_add_u32 m0, s84, 0xee0
	s_nop 0
	global_load_lds_dword v230, s[82:83]
	s_add_u32 s82, s82, 0x1000
	s_addc_u32 s83, s83, 0
	s_add_u32 m0, s84, 0xff0
	s_nop 0
	global_load_lds_dword v230, s[82:83]
	s_add_u32 s82, s82, 0x1000
	s_addc_u32 s83, s83, 0
	s_add_u32 m0, s84, 0x1100
	s_nop 0
	global_load_lds_dword v230, s[82:83]
	s_add_u32 s82, s82, 0x1000
	s_addc_u32 s83, s83, 0
	s_add_u32 m0, s84, 0x1210
	s_nop 0
	global_load_lds_dword v230, s[82:83]
	s_add_u32 s82, s82, 0x1000
	s_addc_u32 s83, s83, 0
	s_add_u32 m0, s84, 0x1320
	s_nop 0
	global_load_lds_dword v230, s[82:83]
	s_add_u32 s82, s82, 0x1000
	s_addc_u32 s83, s83, 0
	s_add_u32 m0, s84, 0x1430
	s_nop 0
	global_load_lds_dword v230, s[82:83]
	s_add_u32 s82, s82, 0x1000
	s_addc_u32 s83, s83, 0
	s_add_u32 m0, s84, 0x1540
	s_nop 0
	global_load_lds_dword v230, s[82:83]
	s_add_u32 s82, s82, 0x1000
	s_addc_u32 s83, s83, 0
	s_add_u32 m0, s84, 0x1650
	s_nop 0
	global_load_lds_dword v230, s[82:83]
	s_add_u32 s82, s82, 0x1000
	s_addc_u32 s83, s83, 0
	s_add_u32 m0, s84, 0x1760
	s_nop 0
	global_load_lds_dword v230, s[82:83]
	s_add_u32 s82, s82, 0x1000
	s_addc_u32 s83, s83, 0
	s_add_u32 m0, s84, 0x1870
	s_nop 0
	global_load_lds_dword v230, s[82:83]
	s_add_u32 s82, s82, 0x1000
	s_addc_u32 s83, s83, 0
	s_add_u32 m0, s84, 0x1980
	s_nop 0
	global_load_lds_dword v230, s[82:83]
	s_add_u32 s82, s82, 0x1000
	s_addc_u32 s83, s83, 0
	s_add_u32 m0, s84, 0x1a90
	s_nop 0
	global_load_lds_dword v230, s[82:83]
	s_add_u32 s82, s82, 0x1000
	s_addc_u32 s83, s83, 0
	s_add_u32 m0, s84, 0x1ba0
	s_nop 0
	global_load_lds_dword v230, s[82:83]
	s_add_u32 s82, s82, 0x1000
	s_addc_u32 s83, s83, 0
	s_add_u32 m0, s84, 0x1cb0
	s_nop 0
	global_load_lds_dword v230, s[82:83]
	s_add_u32 s82, s82, 0x1000
	s_addc_u32 s83, s83, 0
	s_add_u32 m0, s84, 0x1dc0
	s_nop 0
	global_load_lds_dword v230, s[82:83]
	s_add_u32 s82, s82, 0x1000
	s_addc_u32 s83, s83, 0
	s_add_u32 m0, s84, 0x1ed0
	s_nop 0
	global_load_lds_dword v230, s[82:83]
	s_add_u32 s82, s82, 0x1000
	s_addc_u32 s83, s83, 0
	s_add_u32 m0, s84, 0x1fe0
	s_nop 0
	global_load_lds_dword v230, s[82:83]
	s_add_u32 s82, s82, 0x1000
	s_addc_u32 s83, s83, 0
	s_add_u32 m0, s84, 0x20f0
	s_nop 0
	global_load_lds_dword v230, s[82:83]
	ds_read_b128 v[64:67], v166 offset:49152
	ds_read_b128 v[68:71], v166 offset:57344
	v_exp_f32_e32 v132, v142
	v_exp_f32_e32 v133, v143
	v_exp_f32_e32 v140, v140
	s_waitcnt lgkmcnt(1)
	v_mfma_f32_32x32x16_bf16 v[80:95], v[64:67], v[124:127], 0
	v_exp_f32_e32 v141, v141
	v_exp_f32_e32 v138, v138
	v_exp_f32_e32 v139, v139
	v_exp_f32_e32 v136, v136
	v_exp_f32_e32 v137, v137
	v_exp_f32_e32 v134, v134
	v_exp_f32_e32 v135, v135
	s_waitcnt lgkmcnt(0)
	v_mfma_f32_32x32x16_bf16 v[64:79], v[68:71], v[124:127], 0
	ds_read_b128 v[124:127], v167 offset:49152
	ds_read_b128 v[162:165], v167 offset:57344
	ds_read_b128 v[178:181], v168 offset:49152
	ds_read_b128 v[198:201], v168 offset:57344
	v_exp_f32_e32 v142, v148
	v_exp_f32_e32 v143, v149
	v_exp_f32_e32 v146, v146
	v_exp_f32_e32 v147, v147
	v_exp_f32_e32 v144, v144
	v_exp_f32_e32 v145, v145
	s_waitcnt lgkmcnt(3)
	v_mfma_f32_32x32x16_bf16 v[80:95], v[124:127], v[120:123], v[80:95]
	ds_read_b128 v[124:127], v169 offset:49152
	ds_read_b128 v[166:169], v169 offset:57344
	ds_read_b128 v[202:205], v170 offset:49152
	ds_read_b128 v[210:213], v170 offset:57344
	ds_read_b128 v[214:217], v171 offset:49152
	ds_read_b128 v[218:221], v171 offset:57344
	ds_read_b128 v[222:225], v172 offset:49152
	ds_read_b128 v[226:229], v172 offset:57344
	s_waitcnt lgkmcnt(10)
	v_mfma_f32_32x32x16_bf16 v[64:79], v[162:165], v[120:123], v[64:79]
	ds_read_b128 v[120:123], v173 offset:49152
	ds_read_b128 v[162:165], v173 offset:57344
	s_waitcnt lgkmcnt(11)
	v_mfma_f32_32x32x16_bf16 v[80:95], v[178:181], v[112:115], v[80:95]
	s_waitcnt lgkmcnt(10)
	v_mfma_f32_32x32x16_bf16 v[64:79], v[198:201], v[112:115], v[64:79]
	v_add_f32_e32 v112, 0, v190
	v_add_f32_e32 v112, v191, v112
	v_add_f32_e32 v112, v192, v112
	v_add_f32_e32 v112, v193, v112
	v_add_f32_e32 v112, v194, v112
	v_add_f32_e32 v112, v196, v112
	v_add_f32_e32 v112, v195, v112
	s_waitcnt lgkmcnt(9)
	v_mfma_f32_32x32x16_bf16 v[80:95], v[124:127], v[116:119], v[80:95]
	v_add_f32_e32 v112, v197, v112
	v_add_f32_e32 v112, v182, v112
	v_add_f32_e32 v112, v183, v112
	v_add_f32_e32 v112, v184, v112
	v_add_f32_e32 v112, v186, v112
	v_add_f32_e32 v112, v185, v112
	v_add_f32_e32 v112, v187, v112
	s_waitcnt lgkmcnt(8)
	v_mfma_f32_32x32x16_bf16 v[64:79], v[166:169], v[116:119], v[64:79]
	v_add_f32_e32 v112, v188, v112
	v_add_f32_e32 v112, v189, v112
	v_add_f32_e32 v112, v132, v112
	v_add_f32_e32 v112, v133, v112
	v_add_f32_e32 v112, v140, v112
	v_add_f32_e32 v112, v141, v112
	v_add_f32_e32 v112, v138, v112
	s_waitcnt lgkmcnt(7)
	v_mfma_f32_32x32x16_bf16 v[80:95], v[202:205], v[108:111], v[80:95]
	v_add_f32_e32 v112, v139, v112
	v_add_f32_e32 v112, v136, v112
	v_add_f32_e32 v112, v137, v112
	v_cvt_pk_bf16_f32 v113, v195, v197
	v_cvt_pk_bf16_f32 v114, v132, v133
	v_cvt_pk_bf16_f32 v115, v140, v141
	v_cvt_pk_bf16_f32 v116, v138, v139
	s_waitcnt lgkmcnt(6)
	v_mfma_f32_32x32x16_bf16 v[64:79], v[210:213], v[108:111], v[64:79]
	v_add_f32_e32 v108, v134, v112
	v_add_f32_e32 v108, v135, v108
	v_add_f32_e32 v108, v142, v108
	v_add_f32_e32 v108, v143, v108
	v_add_f32_e32 v108, v146, v108
	v_add_f32_e32 v108, v147, v108
	v_add_f32_e32 v108, v144, v108
	s_waitcnt lgkmcnt(5)
	v_mfma_f32_32x32x16_bf16 v[80:95], v[214:217], v[104:107], v[80:95]
	v_add_f32_e32 v108, v145, v108
	v_mov_b32_e32 v109, v108
	s_nop 1
	v_permlane32_swap_b32_e32 v108, v109
	v_cvt_pk_bf16_f32 v110, v190, v191
	v_cvt_pk_bf16_f32 v111, v192, v193
	v_cvt_pk_bf16_f32 v112, v194, v196
	s_waitcnt lgkmcnt(4)
	v_mfma_f32_32x32x16_bf16 v[64:79], v[218:221], v[104:107], v[64:79]
	v_cvt_pk_bf16_f32 v104, v182, v183
	v_cvt_pk_bf16_f32 v105, v184, v186
	v_cvt_pk_bf16_f32 v106, v185, v187
	v_cvt_pk_bf16_f32 v107, v188, v189
	v_cvt_pk_bf16_f32 v117, v136, v137
	s_waitcnt lgkmcnt(3)
	v_mfma_f32_32x32x16_bf16 v[80:95], v[222:225], v[100:103], v[80:95]
	s_waitcnt lgkmcnt(2)
	v_mfma_f32_32x32x16_bf16 v[64:79], v[226:229], v[100:103], v[64:79]
	v_cvt_pk_bf16_f32 v100, v134, v135
	v_cvt_pk_bf16_f32 v101, v142, v143
	v_cvt_pk_bf16_f32 v102, v146, v147
	v_cvt_pk_bf16_f32 v103, v144, v145
	s_waitcnt lgkmcnt(1)
	v_mfma_f32_32x32x16_bf16 v[80:95], v[120:123], v[96:99], v[80:95]
	s_waitcnt lgkmcnt(0)
	v_mfma_f32_32x32x16_bf16 v[64:79], v[162:165], v[96:99], v[64:79]
	ds_read_b64_tr_b16 v[96:97], v161 offset:0
	ds_read_b64_tr_b16 v[98:99], v161 offset:0x800
	ds_read_b64_tr_b16 v[118:119], v161 offset:0x1000
	ds_read_b64_tr_b16 v[120:121], v161 offset:0x1800
	ds_read_b64_tr_b16 v[122:123], v161 offset:0x2000
	ds_read_b64_tr_b16 v[124:125], v161 offset:0x2800
	ds_read_b64_tr_b16 v[132:133], v161 offset:0x3000
	ds_read_b64_tr_b16 v[134:135], v161 offset:0x3800
	s_waitcnt lgkmcnt(0)
	s_nop 0
	v_mfma_f32_32x32x16_bf16 v[0:15], v[110:113], v[96:99], v[0:15]
	ds_read_b64_tr_b16 v[96:97], v161 offset:0x200
	ds_read_b64_tr_b16 v[98:99], v161 offset:0xa00
	v_mfma_f32_32x32x16_bf16 v[0:15], v[104:107], v[118:121], v[0:15]
	ds_read_b64_tr_b16 v[118:119], v161 offset:0x1200
	ds_read_b64_tr_b16 v[120:121], v161 offset:0x1a00
	v_mfma_f32_32x32x16_bf16 v[0:15], v[114:117], v[122:125], v[0:15]
	ds_read_b64_tr_b16 v[122:123], v161 offset:0x2200
	ds_read_b64_tr_b16 v[124:125], v161 offset:0x2a00
	ds_read_b64_tr_b16 v[136:137], v161 offset:0x3200
	ds_read_b64_tr_b16 v[138:139], v161 offset:0x3a00
	s_waitcnt lgkmcnt(0)
	v_mfma_f32_32x32x16_bf16 v[0:15], v[100:103], v[132:135], v[0:15]
	v_mfma_f32_32x32x16_bf16 v[48:63], v[110:113], v[96:99], v[48:63]
	ds_read_b64_tr_b16 v[96:97], v161 offset:0x400
	ds_read_b64_tr_b16 v[98:99], v161 offset:0xc00
	v_mfma_f32_32x32x16_bf16 v[48:63], v[104:107], v[118:121], v[48:63]
	ds_read_b64_tr_b16 v[118:119], v161 offset:0x1400
	ds_read_b64_tr_b16 v[120:121], v161 offset:0x1c00
	v_mfma_f32_32x32x16_bf16 v[48:63], v[114:117], v[122:125], v[48:63]
	ds_read_b64_tr_b16 v[122:123], v161 offset:0x2400
	ds_read_b64_tr_b16 v[124:125], v161 offset:0x2c00
	ds_read_b64_tr_b16 v[132:133], v161 offset:0x3400
	ds_read_b64_tr_b16 v[134:135], v161 offset:0x3c00
	s_waitcnt lgkmcnt(0)
	v_mfma_f32_32x32x16_bf16 v[48:63], v[100:103], v[136:139], v[48:63]
	v_mfma_f32_32x32x16_bf16 v[32:47], v[110:113], v[96:99], v[32:47]
	ds_read_b64_tr_b16 v[96:97], v161 offset:0x600
	ds_read_b64_tr_b16 v[98:99], v161 offset:0xe00
	v_mfma_f32_32x32x16_bf16 v[32:47], v[104:107], v[118:121], v[32:47]
	ds_read_b64_tr_b16 v[118:119], v161 offset:0x1600
	ds_read_b64_tr_b16 v[120:121], v161 offset:0x1e00
	v_mfma_f32_32x32x16_bf16 v[32:47], v[114:117], v[122:125], v[32:47]
	ds_read_b64_tr_b16 v[122:123], v161 offset:0x2600
	ds_read_b64_tr_b16 v[124:125], v161 offset:0x2e00
	ds_read_b64_tr_b16 v[136:137], v161 offset:0x3600
	ds_read_b64_tr_b16 v[138:139], v161 offset:0x3e00
	s_waitcnt lgkmcnt(0)
	v_mfma_f32_32x32x16_bf16 v[32:47], v[100:103], v[132:135], v[32:47]
	v_mfma_f32_32x32x16_bf16 v[16:31], v[110:113], v[96:99], v[16:31]
	v_max_f32_e32 v126, v81, v81
	v_max_f32_e32 v127, v80, v80
	v_max_f32_e32 v126, v127, v126
	v_max3_f32 v126, v126, v82, v83
	v_max3_f32 v126, v126, v84, v85
	v_max3_f32 v96, v126, v86, v87
	v_max3_f32 v96, v96, v88, v89
	v_max3_f32 v96, v96, v90, v91
	v_mfma_f32_32x32x16_bf16 v[16:31], v[104:107], v[118:121], v[16:31]
	v_max3_f32 v96, v96, v92, v93
	v_max3_f32 v96, v96, v94, v95
	v_max3_f32 v96, v96, v64, v65
	v_max3_f32 v96, v96, v66, v67
	v_max3_f32 v96, v96, v68, v69
	v_max3_f32 v96, v96, v70, v71
	v_max3_f32 v96, v96, v72, v73
	v_max3_f32 v96, v96, v74, v75
	v_mfma_f32_32x32x16_bf16 v[16:31], v[114:117], v[122:125], v[16:31]
	v_max3_f32 v96, v96, v76, v77
	v_max3_f32 v96, v96, v78, v79
	v_mov_b32_e32 v97, v96
	s_nop 1
	v_permlane32_swap_b32_e32 v96, v97
	v_max_f32_e32 v97, v97, v97
	v_max_f32_e32 v96, v96, v96
	v_max_f32_e32 v96, v96, v97
	v_max_f32_e32 v97, v175, v175
	v_max_f32_e32 v97, v97, v96
	v_sub_f32_e32 v98, v96, v175
	v_mfma_f32_32x32x16_bf16 v[16:31], v[100:103], v[136:139], v[16:31]
	v_sub_f32_e32 v96, v175, v97
	v_mul_f32_e32 v96, 0x3e0293ee, v96
	v_exp_f32_e32 v96, v96
	v_cmp_ge_f32_e32 vcc, s15, v98
	s_cmp_eq_u64 vcc, exec
	s_cselect_b64 s[8:9], -1, 0
	v_cndmask_b32_e64 v96, v96, 1.0, s[8:9]
	v_cmp_gt_f32_e32 vcc, 1.0, v96
	s_barrier
	s_cbranch_vccz .LBB0_447
	s_and_saveexec_b64 s[2:3], s[6:7]
	ds_write_b32 v158, v96 offset:128
	s_or_b64 exec, exec, s[2:3]
	s_waitcnt lgkmcnt(0)
	v_add_u32_e32 v106, v131, v128
	ds_read_b128 v[98:101], v106 offset:224
	ds_read_b128 v[102:105], v106 offset:192
	ds_read_b128 v[110:113], v106 offset:160
	ds_read_b128 v[114:117], v106 offset:128
	s_waitcnt lgkmcnt(3)
	v_pk_mul_f32 v[12:13], v[12:13], v[98:99]
	s_waitcnt lgkmcnt(2)
	v_pk_mul_f32 v[8:9], v[8:9], v[102:103]
	s_waitcnt lgkmcnt(1)
	v_pk_mul_f32 v[4:5], v[4:5], v[110:111]
	v_pk_mul_f32 v[14:15], v[14:15], v[100:101]
	v_pk_mul_f32 v[10:11], v[10:11], v[104:105]
	v_pk_mul_f32 v[6:7], v[6:7], v[112:113]
	s_waitcnt lgkmcnt(0)
	v_pk_mul_f32 v[2:3], v[2:3], v[116:117]
	v_pk_mul_f32 v[0:1], v[0:1], v[114:115]
	v_pk_mul_f32 v[60:61], v[60:61], v[98:99]
	v_pk_mul_f32 v[56:57], v[56:57], v[102:103]
	v_pk_mul_f32 v[52:53], v[52:53], v[110:111]
	v_pk_mul_f32 v[62:63], v[62:63], v[100:101]
	v_pk_mul_f32 v[58:59], v[58:59], v[104:105]
	v_pk_mul_f32 v[54:55], v[54:55], v[112:113]
	v_pk_mul_f32 v[50:51], v[50:51], v[116:117]
	v_pk_mul_f32 v[48:49], v[48:49], v[114:115]
	v_pk_mul_f32 v[44:45], v[44:45], v[98:99]
	v_pk_mul_f32 v[40:41], v[40:41], v[102:103]
	v_pk_mul_f32 v[36:37], v[36:37], v[110:111]
	v_pk_mul_f32 v[46:47], v[46:47], v[100:101]
	v_pk_mul_f32 v[42:43], v[42:43], v[104:105]
	v_pk_mul_f32 v[38:39], v[38:39], v[112:113]
	v_pk_mul_f32 v[34:35], v[34:35], v[116:117]
	v_pk_mul_f32 v[32:33], v[32:33], v[114:115]
	v_pk_mul_f32 v[28:29], v[28:29], v[98:99]
	v_pk_mul_f32 v[24:25], v[24:25], v[102:103]
	v_pk_mul_f32 v[20:21], v[20:21], v[110:111]
	v_pk_mul_f32 v[30:31], v[30:31], v[100:101]
	v_pk_mul_f32 v[26:27], v[26:27], v[104:105]
	v_pk_mul_f32 v[22:23], v[22:23], v[112:113]
	v_pk_mul_f32 v[18:19], v[18:19], v[116:117]
	v_pk_mul_f32 v[16:17], v[16:17], v[114:115]
